# v1 + dilated loop moved into the MLA phase (two WG groups) + static s_setprio 1 for waves 4-7 in MLA and dilated loops
# speedup vs baseline: 1.0255x; 1.0126x over previous
; #define LAS __attribute__((address_space(3)))
; __global__ void __launch_bounds__(512, 2) fwd_megakernel(Params P) {
;     extern __shared__ __attribute__((aligned(16))) unsigned char lds[];
;     cg::grid_group grid = cg::this_grid();
;     const int G = gridDim.x, bid = blockIdx.x;
;     LAS unsigned char* ring = (LAS unsigned char*)lds;
;     if (threadIdx.x < 16) ((LAS unsigned*)(ring + MISC_OFF))[threadIdx.x] = 0u;
;     __syncthreads();
;     if (bid == 0) for (int i = threadIdx.x; i < (int)(CTL_BYTES + 32768) / 4; i += 512) __hip_atomic_store((unsigned*)(P.ws + WS_CTL) + i, 0u, __ATOMIC_RELAXED, __HIP_MEMORY_SCOPE_AGENT);
_Z14fwd_megakernel6Params:
	s_load_dwordx16 s[12:27], s[0:1], 0x80
	s_mov_b64 s[98:99], s[0:1]
	s_add_u32 s4, s0, 0xc0
	v_and_b32_e32 v242, 0x3ff, v0
	s_mov_b32 s33, s2
	s_addc_u32 s5, s1, 0
	v_cmp_gt_u32_e32 vcc, 16, v242
	s_and_saveexec_b64 s[2:3], vcc
	v_lshl_add_u32 v1, v242, 2, 0
	v_add_u32_e32 v1, 0x20800, v1
	v_mov_b32_e32 v2, 0
	ds_write_b32 v1, v2
	s_or_b64 exec, exec, s[2:3]
	s_load_dwordx2 s[34:35], s[0:1], 0xc0
	s_load_dword s54, s[0:1], 0xc8
	s_cmp_lg_u32 s33, 0
	s_waitcnt lgkmcnt(0)
	s_barrier
	s_cbranch_scc1 .LBB0_6
	v_lshlrev_b32_e32 v2, 2, v242
	v_mov_b32_e32 v3, 0
	v_lshl_add_u64 v[4:5], s[26:27], 0, v[2:3]
	s_mov_b64 s[2:3], 0x1f00000
	v_add_u32_e32 v1, 0xfffffe00, v242
	v_lshl_add_u64 v[4:5], v[4:5], 0, s[2:3]
	s_mov_b64 s[2:3], 0
	s_mov_b64 s[6:7], 0x800
	s_movk_i32 s8, 0x2dff

; __device__ __forceinline__ unsigned xb_ld(unsigned* p)              { return __hip_atomic_load(p, __ATOMIC_RELAXED, __HIP_MEMORY_SCOPE_AGENT); }
; __device__ __forceinline__ void xcd_barrier_complete(unsigned* bar, unsigned x, unsigned& nloc, unsigned& nx) {
;     const unsigned G = gridDim.x * gridDim.y * gridDim.z;
;     unsigned sum, cnt, mine, sp = 0u;
;     for (;;) {
;         sum = 0u; cnt = 0u; mine = 0u;
; #pragma unroll
;         for (unsigned j = 0; j < 16; ++j) { const unsigned c = xb_ld(&bar[XB_XCNT(j)]); sum += c; cnt += (c > 0u) ? 1u : 0u; mine = (j == x) ? c : mine; }
;         if (sum == G) break;
; __device__ __forceinline__ void xcd_barrier(const XcdBarrier& b) {
;     asm volatile("s_waitcnt vmcnt(0)" ::: "memory");
;     __syncthreads();
;     if (threadIdx.x == 0) {
;         unsigned* bar = b.bar;
;         __builtin_amdgcn_s_waitcnt(0);
;         unsigned nloc = b.st[0], nx = b.st[1];
;         if (nloc == 0u) { xcd_barrier_complete(bar, b.x, nloc, nx); b.st[0] = nloc; b.st[1] = nx; }
.LBB0_855:
.LBB0_872:
	s_waitcnt vmcnt(0)
	s_barrier
	s_mov_b64 s[2:3], exec
	v_readlane_b32 s0, v254, 18
	v_readlane_b32 s1, v254, 19
	s_and_b64 s[0:1], s[2:3], s[0:1]
	s_mov_b64 exec, s[0:1]
	s_cbranch_execz .LBB0_924
	s_add_i32 s0, 0, 0x20800
	v_mov_b32_e32 v0, s0
	s_waitcnt vmcnt(0) expcnt(0) lgkmcnt(0)
	ds_read_b32 v2, v0
	s_add_i32 s0, 0, 0x20804
	v_mov_b32_e32 v0, s0
	ds_read_b32 v0, v0
	s_waitcnt lgkmcnt(1)
	v_cmp_ne_u32_e32 vcc, 0, v2
	s_cbranch_vccnz .LBB0_888
	s_add_u32 s4, s26, 0x1f00200
	s_addc_u32 s5, s27, 0
	s_add_u32 s6, s26, 0x1f00400
	s_addc_u32 s7, s27, 0
	s_add_u32 s8, s26, 0x1f00500
	s_addc_u32 s9, s27, 0
	s_add_u32 s14, s26, 0x1f00600
	s_addc_u32 s15, s27, 0
	s_add_u32 s16, s26, 0x1f00700
	s_addc_u32 s17, s27, 0
	s_add_u32 s18, s26, 0x1f00800
	s_addc_u32 s19, s27, 0
	s_add_u32 s20, s26, 0x1f00900
	s_addc_u32 s21, s27, 0
	s_add_u32 s38, s26, 0x1f00a00
	s_addc_u32 s39, s27, 0
	s_add_u32 s40, s26, 0x1f00b00
	s_addc_u32 s41, s27, 0
	s_add_u32 s42, s26, 0x1f00c00
	s_addc_u32 s43, s27, 0
	s_add_u32 s44, s26, 0x1f00d00
	s_addc_u32 s45, s27, 0
	s_add_u32 s46, s26, 0x1f00e00
	s_addc_u32 s47, s27, 0
	s_add_u32 s48, s26, 0x1f00f00
	s_addc_u32 s49, s27, 0
	s_add_u32 s50, s26, 0x1f01000
	s_addc_u32 s51, s27, 0
	s_add_u32 s52, s26, 0x1f01100
	s_addc_u32 s53, s27, 0
	s_add_u32 s58, s26, 0x1f01200
	s_addc_u32 s59, s27, 0
	s_mul_i32 s0, s35, s54
	s_add_u32 s60, s26, 0x1f01300
	s_mul_i32 s0, s0, s34
	s_addc_u32 s61, s27, 0
	s_mov_b32 s1, 1
	v_mov_b32_e32 v16, 0
	s_branch .LBB0_876

; #define REP(k) for (int rep_ = 0; rep_ < (((PHREP >> (k)) & 1) ? 2 : 1); ++rep_)
; #define SEAM() xcd_barrier(xbar)
; __global__ void __launch_bounds__(512, 2) fwd_megakernel(Params P) {
;     ...
;         if (PH(18)) for (int u = bid; u < 3072; u += G) {
;             const int br = u >> 10, v = u & 1023, h = v & 7, w = v >> 3;
;             const int b = w >> 4, blk = w & 15;
;             int d, r, qb; if (br == 0) { d = 1; r = 0; qb = blk; } else if (br == 1) { d = 4; r = blk & 3; qb = blk >> 2; } else { d = 16; r = blk; qb = 0; }
;             const float slope = __builtin_exp2f(-(float)(h + 1));
;             dil::unit(QKV, P.pos, OA + (size_t)br * T * 512, LSE + (size_t)br * T * 8, b, h, d, r, qb, slope, (char*)lds);
;         }
;     }
;     SEAM();
;     if (PH(3)) REP(3) { PHASE_VARS
;     for (int u = bid; u < 512; u += G) {
.LBB0_924:
	s_or_b64 exec, exec, s[2:3]
	s_cmpk_lt_i32 s33, 0x200
	s_mov_b32 s55, s54
	s_mov_b32 s54, s96
	s_cselect_b64 s[8:9], -1, 0
	s_cmpk_gt_i32 s33, 0x1ff
	s_waitcnt lgkmcnt(0)
	v_mov_b32_e32 v0, v242
	s_mov_b64 s[4:5], 0
	s_barrier
	s_cbranch_scc1 .LBB0_938
	s_lshr_b32 s100, s33, 7
	s_cmp_lg_u32 s100, 0
	s_cbranch_scc1 .Lmla_pre
.Ldil_entry:
	v_readfirstlane_b32 s101, v242
	s_lshr_b32 s101, s101, 6
	s_cmp_ge_u32 s101, 4
	s_cbranch_scc0 .Ldil_noprio
	s_setprio 1
.Ldil_noprio:
	s_cmpk_gt_i32 s33, 0xbff
	s_cbranch_scc1 .Ldil_done
	s_add_u32 s0, s26, 0x9c00000
	s_addc_u32 s1, s27, 0
	s_add_u32 s10, s26, 0xfc00000
	s_addc_u32 s11, s27, 0
	s_add_u32 s13, s26, 0x7400000
	s_addc_u32 s38, s27, 0
	s_mov_b32 s9, 0
	s_load_dwordx2 s[40:41], s[98:99], 0x10
	s_movk_i32 s39, 0x70
	s_movk_i32 s42, 0x180
	v_mov_b32_e32 v93, 0
	s_mov_b32 s43, 0x42fc0000
	s_movk_i32 s44, 0x60
	s_mov_b32 s45, 0xf149f2ca
	v_mov_b32_e32 v96, 0x42800000
	s_add_i32 s46, 0, 0x18000
	v_mov_b32_e32 v97, 0xf149f2ca
	v_lshrrev_b32_e32 v234, 3, v242
	v_lshlrev_b32_e32 v235, 4, v242
	v_and_b32_e32 v235, 0x70, v235
	v_lshrrev_b32_e32 v222, 1, v234
	v_and_b32_e32 v222, 7, v222
	v_lshlrev_b32_e32 v222, 4, v222
	v_xor_b32_e32 v222, v222, v235
	v_lshl_or_b32 v222, v234, 7, v222
	v_and_b32_e32 v223, 51, v234
	v_and_b32_e32 v224, 4, v234
	v_lshlrev_b32_e32 v224, 1, v224
	v_or_b32_e32 v223, v223, v224
	v_and_b32_e32 v224, 8, v234
	v_lshrrev_b32_e32 v224, 1, v224
	v_or_b32_e32 v223, v223, v224
	v_lshrrev_b32_e32 v224, 3, v223
	v_lshlrev_b32_e32 v224, 1, v224
	v_bfe_u32 v225, v242, 2, 1
	v_add_u32_e32 v224, v224, v225
	v_lshlrev_b32_e32 v224, 9, v224
	v_and_b32_e32 v225, 7, v223
	v_lshlrev_b32_e32 v225, 5, v225
	v_and_b32_e32 v226, 3, v242
	v_lshl_or_b32 v225, v226, 3, v225
	v_lshlrev_b32_e32 v225, 1, v225
	v_add_u32_e32 v223, v224, v225
	v_add_u32_e32 v223, 0xc000, v223
	s_waitcnt lgkmcnt(0)
	s_mov_b32 s47, s33
	s_branch .LBB0_858

; #define REP(k) for (int rep_ = 0; rep_ < (((PHREP >> (k)) & 1) ? 2 : 1); ++rep_)
; __global__ void __launch_bounds__(512, 2) fwd_megakernel(Params P) {
;     ...
;     if (PH(3)) REP(3) { PHASE_VARS
;     for (int u = bid; u < 512; u += G) {
;         const int bh = (u & 7) * 4 + (u >> 8) * 2 + (((u >> 3) & 31) >> 4), qb = (u >> 3) & 15, b = bh >> 2, h = bh & 3;
.Ldil_done:
	s_setprio 0
	s_cmpk_lt_i32 s33, 0x200
	s_cselect_b64 s[8:9], -1, 0
	s_mov_b64 s[4:5], 0
	s_cmp_lg_u32 s100, 0
	s_cbranch_scc1 .LBB0_938

; __device__ __forceinline__ int opaque_tid() { int t = threadIdx.x; asm volatile("" : "+v"(t)); return t; }
; template <int NPE, int LDQ, int LDK, int VOFF, int LDO> ...
;   const int tid = opaque_tid(), wid = tid >> 6, lane = tid & 63, r32 = lane & 31, hi = lane >> 5;
; __global__ void __launch_bounds__(512, 2) fwd_megakernel(Params P) {
;     ...
;     for (int u = bid; u < 512; u += G) {
;         const int bh = (u & 7) * 4 + (u >> 8) * 2 + (((u >> 3) & 31) >> 4), qb = (u >> 3) & 15, b = bh >> 2, h = bh & 3;
;         const size_t t0 = (size_t)b * SEQ;
;         att::dense_ring<4, 768, 1024, 128, 512>(QB + (t0 + qb * 256) * 768 + h * 192, KVB + t0 * 1024 + h * 256, KPE + t0 * 64, TC + (t0 + qb * 256) * 32, TS + (t0 + qb * 256) * 32,
;                                            OB + (t0 + qb * 256) * 512 + h * 128, SEQ, 0.07216878364870323f, (char*)lds);
.Lmla_noprio:
	s_add_u32 s0, s26, s4
	s_addc_u32 s1, s27, s5
	s_add_u32 s13, s0, 0x7000000
	s_addc_u32 s21, s1, 0
	s_add_u32 s80, s0, 0x7c00000
	s_addc_u32 s81, s1, 0
	s_add_u32 s82, s0, 0x15c00000
	s_addc_u32 s83, s1, 0
	s_add_u32 s84, s0, 0x19c00000
	s_addc_u32 s85, s1, 0
	s_add_u32 s86, s0, 0x6800000
	s_addc_u32 s87, s1, 0
	s_add_u32 s88, s0, 0x6c00000
	s_addc_u32 s89, s1, 0
	s_mov_b32 s60, 0
	v_mov_b32_e32 v145, 0
	s_mov_b64 s[6:7], 0x180
	s_mov_b64 s[14:15], 0x2000
	s_movk_i32 s90, 0x300
	s_mov_b64 s[16:17], 0x40000
	s_mov_b64 s[18:19], 0x4000
	s_mov_b32 s91, 0x42ddb3d8
	s_mov_b32 s20, 0x3dd53b94
	v_mov_b32_e32 v149, 0xf149f2ca
	s_movk_i32 s92, 0x2000
	s_mov_b64 s[38:39], 0x15c60100
	s_mov_b64 s[40:41], 0x15c60000
	s_mov_b64 s[42:43], 0x15c60180
	s_mov_b64 s[44:45], 0x7006000
	s_mov_b64 s[46:47], 0x15c80100
	s_mov_b64 s[48:49], 0x15c80000
	s_mov_b64 s[50:51], 0x15c80180
	s_mov_b64 s[52:53], 0x7008000
	s_add_i32 s93, 0, 0x4000
	s_add_i32 s94, 0, 0x8000
	s_add_i32 s95, 0, 0xa000
	s_add_i32 s96, 0, 0xe000
	s_add_i32 s97, 0, 0x12000
	s_add_i32 s11, 0, 0x14000
	s_mov_b32 s10, s33
	s_branch .LBB0_927

; #define REP(k) for (int rep_ = 0; rep_ < (((PHREP >> (k)) & 1) ? 2 : 1); ++rep_)
; __global__ void __launch_bounds__(512, 2) fwd_megakernel(Params P) {
;     ...
;     if (PH(3)) REP(3) { PHASE_VARS
;     for (int u = bid; u < 512; u += G) {
;         const int bh = (u & 7) * 4 + (u >> 8) * 2 + (((u >> 3) & 31) >> 4), qb = (u >> 3) & 15, b = bh >> 2, h = bh & 3;
;         const size_t t0 = (size_t)b * SEQ;
;         att::dense_ring<4, 768, 1024, 128, 512>(QB + (t0 + qb * 256) * 768 + h * 192, KVB + t0 * 1024 + h * 256, KPE + t0 * 64, TC + (t0 + qb * 256) * 32, TS + (t0 + qb * 256) * 32,
;                                            OB + (t0 + qb * 256) * 512 + h * 128, SEQ, 0.07216878364870323f, (char*)lds);
;     } }
.Lmla_exit:
	s_setprio 0
	s_cmp_eq_u32 s100, 0
	s_cbranch_scc1 .LBB0_938
	s_branch .Ldil_entry

; __global__ void __launch_bounds__(512, 2) fwd_megakernel(Params P) {
	.amdhsa_kernel _Z14fwd_megakernel6Params
		.amdhsa_group_segment_fixed_size 0
		.amdhsa_private_segment_fixed_size 0
		.amdhsa_kernarg_size 448
		.amdhsa_user_sgpr_count 2
		.amdhsa_user_sgpr_dispatch_ptr 0
		.amdhsa_user_sgpr_queue_ptr 0
		.amdhsa_user_sgpr_kernarg_segment_ptr 1
		.amdhsa_user_sgpr_dispatch_id 0
		.amdhsa_user_sgpr_kernarg_preload_length 0
		.amdhsa_user_sgpr_kernarg_preload_offset 0
		.amdhsa_user_sgpr_private_segment_size 0
		.amdhsa_uses_dynamic_stack 0
		.amdhsa_enable_private_segment 0
		.amdhsa_system_sgpr_workgroup_id_x 1
		.amdhsa_system_sgpr_workgroup_id_y 0
		.amdhsa_system_sgpr_workgroup_id_z 0
		.amdhsa_system_sgpr_workgroup_info 0
		.amdhsa_system_vgpr_workitem_id 2
		.amdhsa_next_free_vgpr 255
		.amdhsa_next_free_sgpr 102
		.amdhsa_accum_offset 256
		.amdhsa_reserve_vcc 1
		.amdhsa_float_round_mode_32 0
		.amdhsa_float_round_mode_16_64 0
		.amdhsa_float_denorm_mode_32 3
		.amdhsa_float_denorm_mode_16_64 3
		.amdhsa_dx10_clamp 1
		.amdhsa_ieee_mode 1
		.amdhsa_fp16_overflow 0
		.amdhsa_tg_split 0
		.amdhsa_exception_fp_ieee_invalid_op 0
		.amdhsa_exception_fp_denorm_src 0
		.amdhsa_exception_fp_ieee_div_zero 0
		.amdhsa_exception_fp_ieee_overflow 0
		.amdhsa_exception_fp_ieee_underflow 0
		.amdhsa_exception_fp_ieee_inexact 0
		.amdhsa_exception_int_div_zero 0
	.end_amdhsa_kernel

; __global__ void __launch_bounds__(512, 2) fwd_megakernel(Params P) {
amdhsa.kernels:
  - .agpr_count:     0
    .args:
      - .offset:         0
        .size:           192
        .value_kind:     by_value
      - .offset:         192
        .size:           4
        .value_kind:     hidden_block_count_x
      - .offset:         196
        .size:           4
        .value_kind:     hidden_block_count_y
      - .offset:         200
        .size:           4
        .value_kind:     hidden_block_count_z
      - .offset:         204
        .size:           2
        .value_kind:     hidden_group_size_x
      - .offset:         206
        .size:           2
        .value_kind:     hidden_group_size_y
      - .offset:         208
        .size:           2
        .value_kind:     hidden_group_size_z
      - .offset:         210
        .size:           2
        .value_kind:     hidden_remainder_x
      - .offset:         212
        .size:           2
        .value_kind:     hidden_remainder_y
      - .offset:         214
        .size:           2
        .value_kind:     hidden_remainder_z
      - .offset:         232
        .size:           8
        .value_kind:     hidden_global_offset_x
      - .offset:         240
        .size:           8
        .value_kind:     hidden_global_offset_y
      - .offset:         248
        .size:           8
        .value_kind:     hidden_global_offset_z
      - .offset:         256
        .size:           2
        .value_kind:     hidden_grid_dims
      - .offset:         280
        .size:           8
        .value_kind:     hidden_multigrid_sync_arg
      - .offset:         312
        .size:           4
        .value_kind:     hidden_dynamic_lds_size
    .group_segment_fixed_size: 0
    .kernarg_segment_align: 8
    .kernarg_segment_size: 448
    .language:       OpenCL C
    .language_version:
      - 2
      - 0
    .max_flat_workgroup_size: 512
    .name:           _Z14fwd_megakernel6Params
    .private_segment_fixed_size: 0
    .sgpr_count:     108
    .sgpr_spill_count: 20
    .symbol:         _Z14fwd_megakernel6Params.kd
    .uniform_work_group_size: 1
    .uses_dynamic_stack: false
    .vgpr_count:     255
    .vgpr_spill_count: 0
    .wavefront_size: 64
